# baseline (speedup 1.0000x reference)
; __device__ __forceinline__ void df_unit_p128(ATT_LAS unsigned char* lds, const bf16_t* Q, const bf16_t* __restrict__ K, const bf16_t* __restrict__ V, bf16_t* O, int b, int h, int qb,
;                                              float lam, float post, const float* __restrict__ sub_g, const int wv) {
;     ...
;     const int kxb = r32 * 256 + (((mp * 8 + hi) ^ (r32 & 15)) * 16);
;     const int vread = D8_V0 + ((lane >> 4) & 1) * 32 + (lane & 3) * 8 + (4 * hi + ((lane & 15) >> 2)) * 64;
.LBB0_220:
	v_lshl_add_u64 v[238:239], s[16:17], 0, v[226:227]
	s_mov_b32 m0, s35
	s_waitcnt vmcnt(0) lgkmcnt(0)
	s_barrier
	ds_read_b128 v[66:69], v248 offset:32768
	ds_read_b128 v[70:73], v249 offset:32768
	ds_read_b128 v[74:77], v250 offset:32768
	ds_read_b128 v[78:81], v251 offset:32768
	v_lshl_add_u64 v[216:217], v[238:239], 0, s[42:43]
	v_lshl_add_u64 v[232:233], s[16:17], 0, v[224:225]
	global_load_lds_dwordx4 v[216:217], off
	s_waitcnt lgkmcnt(3)
	v_mfma_f32_32x32x16_bf16 v[114:129], v[66:69], v[154:157], 0
	ds_read_b128 v[66:69], v248 offset:40960
	s_waitcnt lgkmcnt(3)
	v_mfma_f32_32x32x16_bf16 v[114:129], v[70:73], v[150:153], v[114:129]
	ds_read_b128 v[70:73], v249 offset:40960
	v_lshl_add_u64 v[216:217], v[232:233], 0, s[42:43]
	s_mov_b32 m0, s36
	v_lshl_add_u64 v[234:235], s[16:17], 0, v[222:223]
	global_load_lds_dwordx4 v[216:217], off
	s_waitcnt lgkmcnt(3)
	v_mfma_f32_32x32x16_bf16 v[114:129], v[74:77], v[146:149], v[114:129]
	ds_read_b128 v[74:77], v250 offset:40960
	s_waitcnt lgkmcnt(3)
	v_mfma_f32_32x32x16_bf16 v[114:129], v[78:81], v[142:145], v[114:129]
	ds_read_b128 v[78:81], v251 offset:40960
	v_lshl_add_u64 v[216:217], v[234:235], 0, s[42:43]
	s_mov_b32 m0, s37
	v_lshl_add_u64 v[236:237], s[16:17], 0, v[220:221]
	global_load_lds_dwordx4 v[216:217], off
	s_waitcnt lgkmcnt(3)
	v_mfma_f32_32x32x16_bf16 v[98:113], v[66:69], v[154:157], 0
	ds_read_b128 v[66:69], v248 offset:49152
	s_waitcnt lgkmcnt(3)
	v_mfma_f32_32x32x16_bf16 v[98:113], v[70:73], v[150:153], v[98:113]
	ds_read_b128 v[70:73], v249 offset:49152
	v_lshl_add_u64 v[216:217], v[236:237], 0, s[42:43]
	s_mov_b32 m0, s38
	v_lshl_add_u64 v[230:231], s[16:17], 0, v[228:229]
	s_mov_b64 s[40:41], 0x12440000
	global_load_lds_dwordx4 v[216:217], off
	s_waitcnt lgkmcnt(3)
	v_mfma_f32_32x32x16_bf16 v[98:113], v[74:77], v[146:149], v[98:113]
	ds_read_b128 v[74:77], v250 offset:49152
	s_waitcnt lgkmcnt(3)
	v_mfma_f32_32x32x16_bf16 v[98:113], v[78:81], v[142:145], v[98:113]
	v_exp_f32_e32 v114, v114
	v_exp_f32_e32 v115, v115
	v_exp_f32_e32 v116, v116
	v_exp_f32_e32 v117, v117
	ds_read_b128 v[78:81], v251 offset:49152
	v_lshl_add_u64 v[216:217], v[230:231], 0, s[40:41]
	s_mov_b32 m0, s19
	s_mov_b64 s[40:41], 0x12448000
	global_load_lds_dwordx4 v[216:217], off
	s_waitcnt lgkmcnt(3)
	v_mfma_f32_32x32x16_bf16 v[82:97], v[66:69], v[154:157], 0
	v_add_f32_e32 v210, v114, v115
	v_add_f32_e32 v211, v117, v116
	v_cvt_pk_bf16_f32 v130, v114, v115
	v_cvt_pk_bf16_f32 v131, v116, v117
	ds_read_b128 v[194:197], v248 offset:57344
	s_waitcnt lgkmcnt(3)
	v_mfma_f32_32x32x16_bf16 v[82:97], v[70:73], v[150:153], v[82:97]
	v_exp_f32_e32 v118, v118
	v_exp_f32_e32 v119, v119
	v_exp_f32_e32 v120, v120
	v_exp_f32_e32 v121, v121
	ds_read_b128 v[198:201], v249 offset:57344
	v_lshl_add_u64 v[216:217], v[230:231], 0, s[40:41]
	s_add_i32 m0, s7, 0x8400
	s_mov_b64 s[40:41], 0x12450000
	global_load_lds_dwordx4 v[216:217], off
	s_waitcnt lgkmcnt(3)
	v_mfma_f32_32x32x16_bf16 v[82:97], v[74:77], v[146:149], v[82:97]
	v_add_f32_e32 v212, v118, v119
	v_add_f32_e32 v210, v212, v210
	v_add_f32_e32 v213, v121, v120
	v_add_f32_e32 v211, v213, v211
	v_cvt_pk_bf16_f32 v132, v118, v119
	v_cvt_pk_bf16_f32 v133, v120, v121
	ds_read_b128 v[202:205], v250 offset:57344
	s_waitcnt lgkmcnt(3)
	v_mfma_f32_32x32x16_bf16 v[82:97], v[78:81], v[142:145], v[82:97]
	v_exp_f32_e32 v122, v122
	v_exp_f32_e32 v123, v123
	v_exp_f32_e32 v124, v124
	v_exp_f32_e32 v125, v125
	ds_read_b128 v[206:209], v251 offset:57344
	v_lshl_add_u64 v[216:217], v[230:231], 0, s[40:41]
	s_add_i32 m0, s7, 0x8800
	s_mov_b64 s[40:41], 0x12458000
	global_load_lds_dwordx4 v[216:217], off
	s_waitcnt lgkmcnt(3)
	v_mfma_f32_32x32x16_bf16 v[66:81], v[194:197], v[154:157], 0
	v_add_f32_e32 v212, v122, v123
	v_add_f32_e32 v210, v212, v210
	v_add_f32_e32 v213, v125, v124
	v_add_f32_e32 v211, v213, v211
	v_cvt_pk_bf16_f32 v134, v122, v123
	v_cvt_pk_bf16_f32 v135, v124, v125
	s_waitcnt lgkmcnt(2)
	v_mfma_f32_32x32x16_bf16 v[66:81], v[198:201], v[150:153], v[66:81]
	v_exp_f32_e32 v126, v126
	v_exp_f32_e32 v127, v127
	v_exp_f32_e32 v128, v128
	v_exp_f32_e32 v129, v129
	v_lshl_add_u64 v[216:217], v[230:231], 0, s[40:41]
	s_add_i32 m0, s7, 0x8c00
	s_mov_b32 s18, s39
	global_load_lds_dwordx4 v[216:217], off
	ds_read_b64_tr_b16 v[214:215], v252
	ds_read_b64_tr_b16 v[216:217], v252 offset:512
	s_waitcnt lgkmcnt(3)
	v_mfma_f32_32x32x16_bf16 v[66:81], v[202:205], v[146:149], v[66:81]
	v_add_f32_e32 v212, v126, v127
	v_add_f32_e32 v210, v212, v210
	v_add_f32_e32 v213, v129, v128
	v_add_f32_e32 v211, v213, v211
	v_cvt_pk_bf16_f32 v136, v126, v127
	v_cvt_pk_bf16_f32 v137, v128, v129
	ds_read_b64_tr_b16 v[114:115], v252 offset:1024
	ds_read_b64_tr_b16 v[116:117], v252 offset:1536
	s_waitcnt lgkmcnt(4)
	v_mfma_f32_32x32x16_bf16 v[66:81], v[206:209], v[142:145], v[66:81]
	v_exp_f32_e32 v98, v98
	v_exp_f32_e32 v99, v99
	v_exp_f32_e32 v100, v100
	v_exp_f32_e32 v101, v101
	s_waitcnt lgkmcnt(2)
	v_mfma_f32_32x32x16_bf16 v[2:17], v[214:217], v[158:161], v[2:17]
	ds_read_b64_tr_b16 v[118:119], v252 offset:2048
	ds_read_b64_tr_b16 v[120:121], v252 offset:2560
	v_add_f32_e32 v212, v98, v99
	v_add_f32_e32 v210, v212, v210
	v_add_f32_e32 v213, v101, v100
	v_add_f32_e32 v211, v213, v211
	v_cvt_pk_bf16_f32 v138, v98, v99
	v_cvt_pk_bf16_f32 v139, v100, v101
	s_waitcnt lgkmcnt(2)
	v_mfma_f32_32x32x16_bf16 v[2:17], v[114:117], v[162:165], v[2:17]
	ds_read_b64_tr_b16 v[214:215], v252 offset:3072
	ds_read_b64_tr_b16 v[216:217], v252 offset:3584
	s_waitcnt lgkmcnt(2)
	v_mfma_f32_32x32x16_bf16 v[2:17], v[118:121], v[166:169], v[2:17]
	ds_read_b64_tr_b16 v[114:115], v252 offset:4096
	ds_read_b64_tr_b16 v[116:117], v252 offset:4608
	v_exp_f32_e32 v102, v102
	v_exp_f32_e32 v103, v103
	v_exp_f32_e32 v104, v104
	v_exp_f32_e32 v105, v105
	s_waitcnt lgkmcnt(2)
	v_mfma_f32_32x32x16_bf16 v[2:17], v[214:217], v[170:173], v[2:17]
	ds_read_b64_tr_b16 v[118:119], v252 offset:5120
	ds_read_b64_tr_b16 v[120:121], v252 offset:5632
	v_add_f32_e32 v212, v102, v103
	v_add_f32_e32 v210, v212, v210
	v_add_f32_e32 v213, v105, v104
	v_add_f32_e32 v211, v213, v211
	v_cvt_pk_bf16_f32 v140, v102, v103
	v_cvt_pk_bf16_f32 v141, v104, v105
	s_waitcnt lgkmcnt(2)
	v_mfma_f32_32x32x16_bf16 v[2:17], v[114:117], v[174:177], v[2:17]
	ds_read_b64_tr_b16 v[214:215], v252 offset:6144
	ds_read_b64_tr_b16 v[216:217], v252 offset:6656
	s_waitcnt lgkmcnt(2)
	v_mfma_f32_32x32x16_bf16 v[2:17], v[118:121], v[178:181], v[2:17]
	ds_read_b64_tr_b16 v[114:115], v252 offset:7168
	ds_read_b64_tr_b16 v[116:117], v252 offset:7680
	v_exp_f32_e32 v106, v106
	v_exp_f32_e32 v107, v107
	v_exp_f32_e32 v108, v108
	v_exp_f32_e32 v109, v109
	s_waitcnt lgkmcnt(2)
	v_mfma_f32_32x32x16_bf16 v[2:17], v[214:217], v[182:185], v[2:17]
	ds_read_b64_tr_b16 v[118:119], v252 offset:8192
	ds_read_b64_tr_b16 v[120:121], v252 offset:8704
	v_add_f32_e32 v212, v106, v107
	v_add_f32_e32 v210, v212, v210
	v_add_f32_e32 v213, v109, v108
	v_add_f32_e32 v211, v213, v211
	v_cvt_pk_bf16_f32 v190, v106, v107
	v_cvt_pk_bf16_f32 v191, v108, v109
	s_waitcnt lgkmcnt(2)
	v_mfma_f32_32x32x16_bf16 v[2:17], v[114:117], v[186:189], v[2:17]
	ds_read_b64_tr_b16 v[214:215], v252 offset:9216
	ds_read_b64_tr_b16 v[216:217], v252 offset:9728
	v_exp_f32_e32 v110, v110
	v_exp_f32_e32 v111, v111
	v_exp_f32_e32 v112, v112
	v_exp_f32_e32 v113, v113
	s_waitcnt lgkmcnt(2)
	v_mfma_f32_32x32x16_bf16 v[50:65], v[118:121], v[158:161], v[50:65]
	ds_read_b64_tr_b16 v[114:115], v252 offset:10240
	ds_read_b64_tr_b16 v[116:117], v252 offset:10752
	s_waitcnt lgkmcnt(2)
	v_mfma_f32_32x32x16_bf16 v[50:65], v[214:217], v[162:165], v[50:65]
	ds_read_b64_tr_b16 v[118:119], v252 offset:11264
	ds_read_b64_tr_b16 v[120:121], v252 offset:11776
	v_add_f32_e32 v212, v110, v111
	v_add_f32_e32 v210, v212, v210
	v_add_f32_e32 v213, v113, v112
	v_add_f32_e32 v211, v213, v211
	v_cvt_pk_bf16_f32 v192, v110, v111
	v_cvt_pk_bf16_f32 v193, v112, v113
	s_waitcnt lgkmcnt(2)
	v_mfma_f32_32x32x16_bf16 v[50:65], v[114:117], v[166:169], v[50:65]
	ds_read_b64_tr_b16 v[214:215], v252 offset:12288
	ds_read_b64_tr_b16 v[216:217], v252 offset:12800
	v_exp_f32_e32 v82, v82
	v_exp_f32_e32 v83, v83
	v_exp_f32_e32 v84, v84
	v_exp_f32_e32 v85, v85
	s_waitcnt lgkmcnt(2)
	v_mfma_f32_32x32x16_bf16 v[50:65], v[118:121], v[170:173], v[50:65]
	ds_read_b64_tr_b16 v[114:115], v252 offset:13312
	ds_read_b64_tr_b16 v[116:117], v252 offset:13824
	s_waitcnt lgkmcnt(2)
	v_mfma_f32_32x32x16_bf16 v[50:65], v[214:217], v[174:177], v[50:65]
	ds_read_b64_tr_b16 v[118:119], v252 offset:14336
	ds_read_b64_tr_b16 v[120:121], v252 offset:14848
	v_add_f32_e32 v212, v82, v83
	v_add_f32_e32 v210, v212, v210
	v_add_f32_e32 v213, v85, v84
	v_add_f32_e32 v211, v213, v211
	v_cvt_pk_bf16_f32 v194, v82, v83
	v_cvt_pk_bf16_f32 v195, v84, v85
	s_waitcnt lgkmcnt(2)
	v_mfma_f32_32x32x16_bf16 v[50:65], v[114:117], v[178:181], v[50:65]
	ds_read_b64_tr_b16 v[214:215], v252 offset:15360
	ds_read_b64_tr_b16 v[216:217], v252 offset:15872
	v_exp_f32_e32 v86, v86
	v_exp_f32_e32 v87, v87
	v_exp_f32_e32 v88, v88
	v_exp_f32_e32 v89, v89
	s_waitcnt lgkmcnt(2)
	v_mfma_f32_32x32x16_bf16 v[50:65], v[118:121], v[182:185], v[50:65]
	ds_read_b64_tr_b16 v[114:115], v252 offset:16384
	ds_read_b64_tr_b16 v[116:117], v252 offset:16896
	v_add_f32_e32 v212, v86, v87
	v_add_f32_e32 v210, v212, v210
	v_add_f32_e32 v213, v89, v88
	v_add_f32_e32 v211, v213, v211
	v_cvt_pk_bf16_f32 v196, v86, v87
	v_cvt_pk_bf16_f32 v197, v88, v89
	s_waitcnt lgkmcnt(2)
	v_mfma_f32_32x32x16_bf16 v[50:65], v[214:217], v[186:189], v[50:65]
	ds_read_b64_tr_b16 v[118:119], v252 offset:17408
	ds_read_b64_tr_b16 v[120:121], v252 offset:17920
	s_waitcnt lgkmcnt(2)
	v_mfma_f32_32x32x16_bf16 v[34:49], v[114:117], v[158:161], v[34:49]
	ds_read_b64_tr_b16 v[214:215], v252 offset:18432
	ds_read_b64_tr_b16 v[216:217], v252 offset:18944
	v_exp_f32_e32 v90, v90
	v_exp_f32_e32 v91, v91
	v_exp_f32_e32 v92, v92
	v_exp_f32_e32 v93, v93
	s_waitcnt lgkmcnt(2)
	v_mfma_f32_32x32x16_bf16 v[34:49], v[118:121], v[162:165], v[34:49]
	ds_read_b64_tr_b16 v[114:115], v252 offset:19456
	ds_read_b64_tr_b16 v[116:117], v252 offset:19968
	v_add_f32_e32 v212, v90, v91
	v_add_f32_e32 v210, v212, v210
	v_add_f32_e32 v213, v93, v92
	v_add_f32_e32 v211, v213, v211
	v_cvt_pk_bf16_f32 v198, v90, v91
	v_cvt_pk_bf16_f32 v199, v92, v93
	s_waitcnt lgkmcnt(2)
	v_mfma_f32_32x32x16_bf16 v[34:49], v[214:217], v[166:169], v[34:49]
	ds_read_b64_tr_b16 v[118:119], v252 offset:20480
	ds_read_b64_tr_b16 v[120:121], v252 offset:20992
	v_exp_f32_e32 v94, v94
	v_exp_f32_e32 v95, v95
	v_exp_f32_e32 v96, v96
	v_exp_f32_e32 v97, v97
	s_waitcnt lgkmcnt(2)
	v_mfma_f32_32x32x16_bf16 v[34:49], v[114:117], v[170:173], v[34:49]
	ds_read_b64_tr_b16 v[214:215], v252 offset:21504
	ds_read_b64_tr_b16 v[216:217], v252 offset:22016
	s_waitcnt lgkmcnt(2)
	v_mfma_f32_32x32x16_bf16 v[34:49], v[118:121], v[174:177], v[34:49]
	ds_read_b64_tr_b16 v[114:115], v252 offset:22528
	ds_read_b64_tr_b16 v[116:117], v252 offset:23040
	v_add_f32_e32 v212, v94, v95
	v_add_f32_e32 v210, v212, v210
	v_add_f32_e32 v213, v97, v96
	v_add_f32_e32 v211, v213, v211
	v_cvt_pk_bf16_f32 v200, v94, v95
	v_cvt_pk_bf16_f32 v201, v96, v97
	s_waitcnt lgkmcnt(2)
	v_mfma_f32_32x32x16_bf16 v[34:49], v[214:217], v[178:181], v[34:49]
	ds_read_b64_tr_b16 v[118:119], v252 offset:23552
	ds_read_b64_tr_b16 v[120:121], v252 offset:24064
	v_exp_f32_e32 v66, v66
	v_exp_f32_e32 v67, v67
	v_exp_f32_e32 v68, v68
	v_exp_f32_e32 v69, v69
	s_waitcnt lgkmcnt(2)
	v_mfma_f32_32x32x16_bf16 v[34:49], v[114:117], v[182:185], v[34:49]
	ds_read_b64_tr_b16 v[214:215], v252 offset:24576
	ds_read_b64_tr_b16 v[216:217], v252 offset:25088
	s_waitcnt lgkmcnt(2)
	v_mfma_f32_32x32x16_bf16 v[34:49], v[118:121], v[186:189], v[34:49]
	ds_read_b64_tr_b16 v[114:115], v252 offset:25600
	ds_read_b64_tr_b16 v[116:117], v252 offset:26112
	v_add_f32_e32 v212, v66, v67
	v_add_f32_e32 v210, v212, v210
	v_add_f32_e32 v213, v69, v68
	v_add_f32_e32 v211, v213, v211
	v_cvt_pk_bf16_f32 v202, v66, v67
	v_cvt_pk_bf16_f32 v203, v68, v69
	s_waitcnt lgkmcnt(2)
	v_mfma_f32_32x32x16_bf16 v[18:33], v[214:217], v[158:161], v[18:33]
	ds_read_b64_tr_b16 v[118:119], v252 offset:26624
	ds_read_b64_tr_b16 v[120:121], v252 offset:27136
	v_exp_f32_e32 v70, v70
	v_exp_f32_e32 v71, v71
	v_exp_f32_e32 v72, v72
	v_exp_f32_e32 v73, v73
	s_waitcnt lgkmcnt(2)
	v_mfma_f32_32x32x16_bf16 v[18:33], v[114:117], v[162:165], v[18:33]
	ds_read_b64_tr_b16 v[214:215], v252 offset:27648
	ds_read_b64_tr_b16 v[216:217], v252 offset:28160
	v_add_f32_e32 v212, v70, v71
	v_add_f32_e32 v210, v212, v210
	v_add_f32_e32 v213, v73, v72
	v_add_f32_e32 v211, v213, v211
	v_cvt_pk_bf16_f32 v204, v70, v71
	v_cvt_pk_bf16_f32 v205, v72, v73
	s_waitcnt lgkmcnt(2)
	v_mfma_f32_32x32x16_bf16 v[18:33], v[118:121], v[166:169], v[18:33]
	ds_read_b64_tr_b16 v[114:115], v252 offset:28672
	ds_read_b64_tr_b16 v[116:117], v252 offset:29184
	s_waitcnt lgkmcnt(2)
	v_mfma_f32_32x32x16_bf16 v[18:33], v[214:217], v[170:173], v[18:33]
	ds_read_b64_tr_b16 v[118:119], v252 offset:29696
	ds_read_b64_tr_b16 v[120:121], v252 offset:30208
	v_exp_f32_e32 v74, v74
	v_exp_f32_e32 v75, v75
	v_exp_f32_e32 v76, v76
	v_exp_f32_e32 v77, v77
	s_waitcnt lgkmcnt(2)
	v_mfma_f32_32x32x16_bf16 v[18:33], v[114:117], v[174:177], v[18:33]
	ds_read_b64_tr_b16 v[214:215], v252 offset:30720
	ds_read_b64_tr_b16 v[216:217], v252 offset:31232
	v_add_f32_e32 v212, v74, v75
	v_add_f32_e32 v210, v212, v210
	v_add_f32_e32 v213, v77, v76
	v_add_f32_e32 v211, v213, v211
	v_cvt_pk_bf16_f32 v206, v74, v75
	v_cvt_pk_bf16_f32 v207, v76, v77
	s_waitcnt lgkmcnt(2)
	v_mfma_f32_32x32x16_bf16 v[18:33], v[118:121], v[178:181], v[18:33]
	ds_read_b64_tr_b16 v[114:115], v252 offset:31744
	ds_read_b64_tr_b16 v[116:117], v252 offset:32256
	s_waitcnt lgkmcnt(2)
	v_mfma_f32_32x32x16_bf16 v[18:33], v[214:217], v[182:185], v[18:33]
	v_exp_f32_e32 v78, v78
	v_exp_f32_e32 v79, v79
	v_exp_f32_e32 v80, v80
	v_exp_f32_e32 v81, v81
	s_waitcnt lgkmcnt(0)
	v_mfma_f32_32x32x16_bf16 v[18:33], v[114:117], v[186:189], v[18:33]
	v_add_f32_e32 v212, v78, v79
	v_add_f32_e32 v210, v212, v210
	v_add_f32_e32 v213, v81, v80
	v_add_f32_e32 v211, v213, v211
	v_cvt_pk_bf16_f32 v208, v78, v79
	v_cvt_pk_bf16_f32 v209, v80, v81
	v_add_f32_e32 v241, v211, v210
	s_waitcnt vmcnt(0) lgkmcnt(0)
	s_barrier
	ds_read_b128 v[66:69], v248
	ds_read_b128 v[70:73], v249
	ds_read_b128 v[74:77], v250
	ds_read_b128 v[78:81], v251
	v_lshl_add_u64 v[216:217], v[238:239], 0, s[44:45]
	s_mov_b32 m0, s33
	s_mov_b64 s[40:41], 0x12480000
	global_load_lds_dwordx4 v[216:217], off
	s_waitcnt lgkmcnt(3)
	v_mfma_f32_32x32x16_bf16 v[114:129], v[66:69], v[154:157], 0
	ds_read_b128 v[66:69], v248 offset:8192
	s_waitcnt lgkmcnt(3)
	v_mfma_f32_32x32x16_bf16 v[114:129], v[70:73], v[150:153], v[114:129]
	ds_read_b128 v[70:73], v249 offset:8192
	v_lshl_add_u64 v[216:217], v[232:233], 0, s[44:45]
	s_add_i32 m0, s35, 0x8400
	global_load_lds_dwordx4 v[216:217], off
	s_waitcnt lgkmcnt(3)
	v_mfma_f32_32x32x16_bf16 v[114:129], v[74:77], v[146:149], v[114:129]
	ds_read_b128 v[74:77], v250 offset:8192
	s_waitcnt lgkmcnt(3)
	v_mfma_f32_32x32x16_bf16 v[114:129], v[78:81], v[142:145], v[114:129]
	ds_read_b128 v[78:81], v251 offset:8192
	v_lshl_add_u64 v[216:217], v[234:235], 0, s[44:45]
	s_add_i32 m0, s35, 0x8800
	s_nop 0
	global_load_lds_dwordx4 v[216:217], off
	s_waitcnt lgkmcnt(3)
	v_mfma_f32_32x32x16_bf16 v[98:113], v[66:69], v[154:157], 0
	ds_read_b128 v[66:69], v248 offset:16384
	s_waitcnt lgkmcnt(3)
	v_mfma_f32_32x32x16_bf16 v[98:113], v[70:73], v[150:153], v[98:113]
	ds_read_b128 v[70:73], v249 offset:16384
	v_lshl_add_u64 v[216:217], v[236:237], 0, s[44:45]
	s_add_i32 m0, s35, 0x8c00
	s_nop 0
	global_load_lds_dwordx4 v[216:217], off
	s_waitcnt lgkmcnt(3)
	v_mfma_f32_32x32x16_bf16 v[98:113], v[74:77], v[146:149], v[98:113]
	ds_read_b128 v[74:77], v250 offset:16384
	s_waitcnt lgkmcnt(3)
	v_mfma_f32_32x32x16_bf16 v[98:113], v[78:81], v[142:145], v[98:113]
	v_exp_f32_e32 v114, v114
	v_exp_f32_e32 v115, v115
	v_exp_f32_e32 v116, v116
	v_exp_f32_e32 v117, v117
	ds_read_b128 v[78:81], v251 offset:16384
	v_lshl_add_u64 v[216:217], v[230:231], 0, s[40:41]
	s_mov_b32 m0, s7
	s_mov_b64 s[40:41], 0x12488000
	global_load_lds_dwordx4 v[216:217], off
	s_waitcnt lgkmcnt(3)
	v_mfma_f32_32x32x16_bf16 v[82:97], v[66:69], v[154:157], 0
	v_add_f32_e32 v210, v114, v115
	v_add_f32_e32 v211, v117, v116
	v_cvt_pk_bf16_f32 v158, v114, v115
	v_cvt_pk_bf16_f32 v159, v116, v117
	ds_read_b128 v[174:177], v248 offset:24576
	s_waitcnt lgkmcnt(3)
	v_mfma_f32_32x32x16_bf16 v[82:97], v[70:73], v[150:153], v[82:97]
	v_exp_f32_e32 v118, v118
	v_exp_f32_e32 v119, v119
	v_exp_f32_e32 v120, v120
	v_exp_f32_e32 v121, v121
	ds_read_b128 v[178:181], v249 offset:24576
	v_lshl_add_u64 v[216:217], v[230:231], 0, s[40:41]
	s_mov_b32 m0, s30
	s_mov_b64 s[40:41], 0x12490000
	global_load_lds_dwordx4 v[216:217], off
	s_waitcnt lgkmcnt(3)
; __device__ __forceinline__ void df_unit_p128(ATT_LAS unsigned char* lds, const bf16_t* Q, const bf16_t* __restrict__ K, const bf16_t* __restrict__ V, bf16_t* O, int b, int h, int qb,
;                                              float lam, float post, const float* __restrict__ sub_g, const int wv) {
;     ...
;     const int kxb = r32 * 256 + (((mp * 8 + hi) ^ (r32 & 15)) * 16);
;     const int vread = D8_V0 + ((lane >> 4) & 1) * 32 + (lane & 3) * 8 + (4 * hi + ((lane & 15) >> 2)) * 64;
	v_mfma_f32_32x32x16_bf16 v[82:97], v[74:77], v[146:149], v[82:97]
	v_add_f32_e32 v212, v118, v119
	v_add_f32_e32 v210, v212, v210
	v_add_f32_e32 v213, v121, v120
	v_add_f32_e32 v211, v213, v211
	v_cvt_pk_bf16_f32 v160, v118, v119
	v_cvt_pk_bf16_f32 v161, v120, v121
	ds_read_b128 v[182:185], v250 offset:24576
	s_waitcnt lgkmcnt(3)
	v_mfma_f32_32x32x16_bf16 v[82:97], v[78:81], v[142:145], v[82:97]
	v_exp_f32_e32 v122, v122
	v_exp_f32_e32 v123, v123
	v_exp_f32_e32 v124, v124
	v_exp_f32_e32 v125, v125
	ds_read_b128 v[186:189], v251 offset:24576
	v_lshl_add_u64 v[216:217], v[230:231], 0, s[40:41]
	s_mov_b32 m0, s31
	s_mov_b64 s[40:41], 0x12498000
	global_load_lds_dwordx4 v[216:217], off
	s_waitcnt lgkmcnt(3)
	v_mfma_f32_32x32x16_bf16 v[66:81], v[174:177], v[154:157], 0
	v_add_f32_e32 v212, v122, v123
	v_add_f32_e32 v210, v212, v210
	v_add_f32_e32 v213, v125, v124
	v_add_f32_e32 v211, v213, v211
	v_cvt_pk_bf16_f32 v162, v122, v123
	v_cvt_pk_bf16_f32 v163, v124, v125
	s_waitcnt lgkmcnt(2)
	v_mfma_f32_32x32x16_bf16 v[66:81], v[178:181], v[150:153], v[66:81]
	v_exp_f32_e32 v126, v126
	v_exp_f32_e32 v127, v127
	v_exp_f32_e32 v128, v128
	v_exp_f32_e32 v129, v129
	v_lshl_add_u64 v[216:217], v[230:231], 0, s[40:41]
	s_mov_b32 m0, s34
	s_nop 0
	global_load_lds_dwordx4 v[216:217], off
	ds_read_b64_tr_b16 v[214:215], v253
	ds_read_b64_tr_b16 v[216:217], v253 offset:512
	s_waitcnt lgkmcnt(3)
	v_mfma_f32_32x32x16_bf16 v[66:81], v[182:185], v[146:149], v[66:81]
	v_add_f32_e32 v212, v126, v127
	v_add_f32_e32 v210, v212, v210
	v_add_f32_e32 v213, v129, v128
	v_add_f32_e32 v211, v213, v211
	v_cvt_pk_bf16_f32 v164, v126, v127
	v_cvt_pk_bf16_f32 v165, v128, v129
	ds_read_b64_tr_b16 v[114:115], v253 offset:1024
	ds_read_b64_tr_b16 v[116:117], v253 offset:1536
	s_waitcnt lgkmcnt(4)
	v_mfma_f32_32x32x16_bf16 v[66:81], v[186:189], v[142:145], v[66:81]
	v_exp_f32_e32 v98, v98
	v_exp_f32_e32 v99, v99
	v_exp_f32_e32 v100, v100
	v_exp_f32_e32 v101, v101
	s_waitcnt lgkmcnt(2)
	v_mfma_f32_32x32x16_bf16 v[2:17], v[214:217], v[130:133], v[2:17]
	ds_read_b64_tr_b16 v[118:119], v253 offset:2048
	ds_read_b64_tr_b16 v[120:121], v253 offset:2560
	v_add_f32_e32 v212, v98, v99
	v_add_f32_e32 v210, v212, v210
	v_add_f32_e32 v213, v101, v100
	v_add_f32_e32 v211, v213, v211
	v_cvt_pk_bf16_f32 v166, v98, v99
	v_cvt_pk_bf16_f32 v167, v100, v101
	s_waitcnt lgkmcnt(2)
	v_mfma_f32_32x32x16_bf16 v[2:17], v[114:117], v[134:137], v[2:17]
	ds_read_b64_tr_b16 v[214:215], v253 offset:3072
	ds_read_b64_tr_b16 v[216:217], v253 offset:3584
	s_waitcnt lgkmcnt(2)
	v_mfma_f32_32x32x16_bf16 v[2:17], v[118:121], v[138:141], v[2:17]
	ds_read_b64_tr_b16 v[114:115], v253 offset:4096
	ds_read_b64_tr_b16 v[116:117], v253 offset:4608
	v_exp_f32_e32 v102, v102
	v_exp_f32_e32 v103, v103
	v_exp_f32_e32 v104, v104
	v_exp_f32_e32 v105, v105
	s_waitcnt lgkmcnt(2)
	v_mfma_f32_32x32x16_bf16 v[2:17], v[214:217], v[190:193], v[2:17]
	ds_read_b64_tr_b16 v[118:119], v253 offset:5120
	ds_read_b64_tr_b16 v[120:121], v253 offset:5632
	v_add_f32_e32 v212, v102, v103
	v_add_f32_e32 v210, v212, v210
	v_add_f32_e32 v213, v105, v104
	v_add_f32_e32 v211, v213, v211
	v_cvt_pk_bf16_f32 v168, v102, v103
	v_cvt_pk_bf16_f32 v169, v104, v105
	s_waitcnt lgkmcnt(2)
	v_mfma_f32_32x32x16_bf16 v[2:17], v[114:117], v[194:197], v[2:17]
	ds_read_b64_tr_b16 v[214:215], v253 offset:6144
	ds_read_b64_tr_b16 v[216:217], v253 offset:6656
	s_waitcnt lgkmcnt(2)
	v_mfma_f32_32x32x16_bf16 v[2:17], v[118:121], v[198:201], v[2:17]
	ds_read_b64_tr_b16 v[114:115], v253 offset:7168
	ds_read_b64_tr_b16 v[116:117], v253 offset:7680
	v_exp_f32_e32 v106, v106
	v_exp_f32_e32 v107, v107
	v_exp_f32_e32 v108, v108
	v_exp_f32_e32 v109, v109
	s_waitcnt lgkmcnt(2)
	v_mfma_f32_32x32x16_bf16 v[2:17], v[214:217], v[202:205], v[2:17]
	ds_read_b64_tr_b16 v[118:119], v253 offset:8192
	ds_read_b64_tr_b16 v[120:121], v253 offset:8704
	v_add_f32_e32 v212, v106, v107
	v_add_f32_e32 v210, v212, v210
	v_add_f32_e32 v213, v109, v108
	v_add_f32_e32 v211, v213, v211
	v_cvt_pk_bf16_f32 v170, v106, v107
	v_cvt_pk_bf16_f32 v171, v108, v109
	s_waitcnt lgkmcnt(2)
	v_mfma_f32_32x32x16_bf16 v[2:17], v[114:117], v[206:209], v[2:17]
	ds_read_b64_tr_b16 v[214:215], v253 offset:9216
	ds_read_b64_tr_b16 v[216:217], v253 offset:9728
	v_exp_f32_e32 v110, v110
	v_exp_f32_e32 v111, v111
	v_exp_f32_e32 v112, v112
	v_exp_f32_e32 v113, v113
	s_waitcnt lgkmcnt(2)
	v_mfma_f32_32x32x16_bf16 v[50:65], v[118:121], v[130:133], v[50:65]
	ds_read_b64_tr_b16 v[114:115], v253 offset:10240
	ds_read_b64_tr_b16 v[116:117], v253 offset:10752
	s_waitcnt lgkmcnt(2)
	v_mfma_f32_32x32x16_bf16 v[50:65], v[214:217], v[134:137], v[50:65]
	ds_read_b64_tr_b16 v[118:119], v253 offset:11264
	ds_read_b64_tr_b16 v[120:121], v253 offset:11776
	v_add_f32_e32 v212, v110, v111
	v_add_f32_e32 v210, v212, v210
	v_add_f32_e32 v213, v113, v112
	v_add_f32_e32 v211, v213, v211
	v_cvt_pk_bf16_f32 v172, v110, v111
	v_cvt_pk_bf16_f32 v173, v112, v113
	s_waitcnt lgkmcnt(2)
	v_mfma_f32_32x32x16_bf16 v[50:65], v[114:117], v[138:141], v[50:65]
	ds_read_b64_tr_b16 v[214:215], v253 offset:12288
	ds_read_b64_tr_b16 v[216:217], v253 offset:12800
	v_exp_f32_e32 v82, v82
	v_exp_f32_e32 v83, v83
	v_exp_f32_e32 v84, v84
	v_exp_f32_e32 v85, v85
	s_waitcnt lgkmcnt(2)
	v_mfma_f32_32x32x16_bf16 v[50:65], v[118:121], v[190:193], v[50:65]
	ds_read_b64_tr_b16 v[114:115], v253 offset:13312
	ds_read_b64_tr_b16 v[116:117], v253 offset:13824
	s_waitcnt lgkmcnt(2)
	v_mfma_f32_32x32x16_bf16 v[50:65], v[214:217], v[194:197], v[50:65]
	ds_read_b64_tr_b16 v[118:119], v253 offset:14336
	ds_read_b64_tr_b16 v[120:121], v253 offset:14848
	v_add_f32_e32 v212, v82, v83
	v_add_f32_e32 v210, v212, v210
	v_add_f32_e32 v213, v85, v84
	v_add_f32_e32 v211, v213, v211
	v_cvt_pk_bf16_f32 v174, v82, v83
	v_cvt_pk_bf16_f32 v175, v84, v85
	s_waitcnt lgkmcnt(2)
; #define D8_FULL(WC_, WN_, t_, MASK_) do { const int tt = (t_); D8_HEAD(tt) D8_QKP(tt + 1, MASK_) D8_PVX(tt, WC_, true, WN_) } while (0)
; __device__ __forceinline__ void df_unit_p128(ATT_LAS unsigned char* lds, const bf16_t* Q, const bf16_t* __restrict__ K, const bf16_t* __restrict__ V, bf16_t* O, int b, int h, int qb,
;                                              float lam, float post, const float* __restrict__ sub_g, const int wv) {
;     ...
;     for (; T + 2 <= qb - 1; T += 2) { D8_FULL(wa, wb, T, false); D8_FULL(wb, wa, T + 1, false); }
	v_mfma_f32_32x32x16_bf16 v[50:65], v[114:117], v[198:201], v[50:65]
	ds_read_b64_tr_b16 v[214:215], v253 offset:15360
	ds_read_b64_tr_b16 v[216:217], v253 offset:15872
	v_exp_f32_e32 v86, v86
	v_exp_f32_e32 v87, v87
	v_exp_f32_e32 v88, v88
	v_exp_f32_e32 v89, v89
	s_waitcnt lgkmcnt(2)
	v_mfma_f32_32x32x16_bf16 v[50:65], v[118:121], v[202:205], v[50:65]
	ds_read_b64_tr_b16 v[114:115], v253 offset:16384
	ds_read_b64_tr_b16 v[116:117], v253 offset:16896
	v_add_f32_e32 v212, v86, v87
	v_add_f32_e32 v210, v212, v210
	v_add_f32_e32 v213, v89, v88
	v_add_f32_e32 v211, v213, v211
	v_cvt_pk_bf16_f32 v176, v86, v87
	v_cvt_pk_bf16_f32 v177, v88, v89
	s_waitcnt lgkmcnt(2)
	v_mfma_f32_32x32x16_bf16 v[50:65], v[214:217], v[206:209], v[50:65]
	ds_read_b64_tr_b16 v[118:119], v253 offset:17408
	ds_read_b64_tr_b16 v[120:121], v253 offset:17920
	s_waitcnt lgkmcnt(2)
	v_mfma_f32_32x32x16_bf16 v[34:49], v[114:117], v[130:133], v[34:49]
	ds_read_b64_tr_b16 v[214:215], v253 offset:18432
	ds_read_b64_tr_b16 v[216:217], v253 offset:18944
	v_exp_f32_e32 v90, v90
	v_exp_f32_e32 v91, v91
	v_exp_f32_e32 v92, v92
	v_exp_f32_e32 v93, v93
	s_waitcnt lgkmcnt(2)
	v_mfma_f32_32x32x16_bf16 v[34:49], v[118:121], v[134:137], v[34:49]
	ds_read_b64_tr_b16 v[114:115], v253 offset:19456
	ds_read_b64_tr_b16 v[116:117], v253 offset:19968
	v_add_f32_e32 v212, v90, v91
	v_add_f32_e32 v210, v212, v210
	v_add_f32_e32 v213, v93, v92
	v_add_f32_e32 v211, v213, v211
	v_cvt_pk_bf16_f32 v178, v90, v91
	v_cvt_pk_bf16_f32 v179, v92, v93
	s_waitcnt lgkmcnt(2)
	v_mfma_f32_32x32x16_bf16 v[34:49], v[214:217], v[138:141], v[34:49]
	ds_read_b64_tr_b16 v[118:119], v253 offset:20480
	ds_read_b64_tr_b16 v[120:121], v253 offset:20992
	v_exp_f32_e32 v94, v94
	v_exp_f32_e32 v95, v95
	v_exp_f32_e32 v96, v96
	v_exp_f32_e32 v97, v97
	s_waitcnt lgkmcnt(2)
	v_mfma_f32_32x32x16_bf16 v[34:49], v[114:117], v[190:193], v[34:49]
	ds_read_b64_tr_b16 v[214:215], v253 offset:21504
	ds_read_b64_tr_b16 v[216:217], v253 offset:22016
	s_waitcnt lgkmcnt(2)
	v_mfma_f32_32x32x16_bf16 v[34:49], v[118:121], v[194:197], v[34:49]
	ds_read_b64_tr_b16 v[114:115], v253 offset:22528
	ds_read_b64_tr_b16 v[116:117], v253 offset:23040
	v_add_f32_e32 v212, v94, v95
	v_add_f32_e32 v210, v212, v210
	v_add_f32_e32 v213, v97, v96
	v_add_f32_e32 v211, v213, v211
	v_cvt_pk_bf16_f32 v180, v94, v95
	v_cvt_pk_bf16_f32 v181, v96, v97
	s_waitcnt lgkmcnt(2)
	v_mfma_f32_32x32x16_bf16 v[34:49], v[214:217], v[198:201], v[34:49]
	ds_read_b64_tr_b16 v[118:119], v253 offset:23552
	ds_read_b64_tr_b16 v[120:121], v253 offset:24064
	v_exp_f32_e32 v66, v66
	v_exp_f32_e32 v67, v67
	v_exp_f32_e32 v68, v68
	v_exp_f32_e32 v69, v69
	s_waitcnt lgkmcnt(2)
	v_mfma_f32_32x32x16_bf16 v[34:49], v[114:117], v[202:205], v[34:49]
	ds_read_b64_tr_b16 v[214:215], v253 offset:24576
	ds_read_b64_tr_b16 v[216:217], v253 offset:25088
	s_waitcnt lgkmcnt(2)
	v_mfma_f32_32x32x16_bf16 v[34:49], v[118:121], v[206:209], v[34:49]
	ds_read_b64_tr_b16 v[114:115], v253 offset:25600
	ds_read_b64_tr_b16 v[116:117], v253 offset:26112
	v_add_f32_e32 v212, v66, v67
	v_add_f32_e32 v210, v212, v210
	v_add_f32_e32 v213, v69, v68
	v_add_f32_e32 v211, v213, v211
	v_cvt_pk_bf16_f32 v182, v66, v67
	v_cvt_pk_bf16_f32 v183, v68, v69
	s_waitcnt lgkmcnt(2)
	v_mfma_f32_32x32x16_bf16 v[18:33], v[214:217], v[130:133], v[18:33]
	ds_read_b64_tr_b16 v[118:119], v253 offset:26624
	ds_read_b64_tr_b16 v[120:121], v253 offset:27136
	v_exp_f32_e32 v70, v70
	v_exp_f32_e32 v71, v71
	v_exp_f32_e32 v72, v72
	v_exp_f32_e32 v73, v73
	s_waitcnt lgkmcnt(2)
	v_mfma_f32_32x32x16_bf16 v[18:33], v[114:117], v[134:137], v[18:33]
	ds_read_b64_tr_b16 v[214:215], v253 offset:27648
	ds_read_b64_tr_b16 v[216:217], v253 offset:28160
	v_add_f32_e32 v212, v70, v71
	v_add_f32_e32 v210, v212, v210
	v_add_f32_e32 v213, v73, v72
	v_add_f32_e32 v211, v213, v211
	v_cvt_pk_bf16_f32 v184, v70, v71
	v_cvt_pk_bf16_f32 v185, v72, v73
	s_waitcnt lgkmcnt(2)
	v_mfma_f32_32x32x16_bf16 v[18:33], v[118:121], v[138:141], v[18:33]
	ds_read_b64_tr_b16 v[114:115], v253 offset:28672
	ds_read_b64_tr_b16 v[116:117], v253 offset:29184
	s_waitcnt lgkmcnt(2)
	v_mfma_f32_32x32x16_bf16 v[18:33], v[214:217], v[190:193], v[18:33]
	ds_read_b64_tr_b16 v[118:119], v253 offset:29696
	ds_read_b64_tr_b16 v[120:121], v253 offset:30208
	v_exp_f32_e32 v74, v74
	v_exp_f32_e32 v75, v75
	v_exp_f32_e32 v76, v76
	v_exp_f32_e32 v77, v77
	s_waitcnt lgkmcnt(2)
	v_mfma_f32_32x32x16_bf16 v[18:33], v[114:117], v[194:197], v[18:33]
	ds_read_b64_tr_b16 v[214:215], v253 offset:30720
	ds_read_b64_tr_b16 v[216:217], v253 offset:31232
	v_add_f32_e32 v212, v74, v75
	v_add_f32_e32 v210, v212, v210
	v_add_f32_e32 v213, v77, v76
	v_add_f32_e32 v211, v213, v211
	v_cvt_pk_bf16_f32 v186, v74, v75
	v_cvt_pk_bf16_f32 v187, v76, v77
	s_waitcnt lgkmcnt(2)
	v_mfma_f32_32x32x16_bf16 v[18:33], v[118:121], v[198:201], v[18:33]
	ds_read_b64_tr_b16 v[114:115], v253 offset:31744
	ds_read_b64_tr_b16 v[116:117], v253 offset:32256
	s_waitcnt lgkmcnt(2)
	v_mfma_f32_32x32x16_bf16 v[18:33], v[214:217], v[202:205], v[18:33]
	v_exp_f32_e32 v78, v78
	v_exp_f32_e32 v79, v79
	v_exp_f32_e32 v80, v80
	v_exp_f32_e32 v81, v81
	s_waitcnt lgkmcnt(0)
	v_mfma_f32_32x32x16_bf16 v[18:33], v[114:117], v[206:209], v[18:33]
	v_add_f32_e32 v212, v78, v79
	v_add_f32_e32 v210, v212, v210
	v_add_f32_e32 v213, v81, v80
	v_add_f32_e32 v211, v213, v211
	v_cvt_pk_bf16_f32 v188, v78, v79
	v_cvt_pk_bf16_f32 v189, v80, v81
	s_add_i32 s39, s39, 2
	s_add_u32 s16, s16, 0x80000
	v_add_f32_e32 v212, v247, v241
	v_add_f32_e32 v213, v211, v210
	s_addc_u32 s17, s17, 0
	s_add_i32 s18, s18, 4
	s_cmp_lt_u32 s18, s25
	v_add_f32_e32 v247, v212, v213
	s_cbranch_scc1 .LBB0_220
	s_nop 0
	s_mov_b32 s19, s55
	s_lshl_b64 s[16:17], s[18:19], 18
	v_mov_b64_e32 v[226:227], 0x600
	v_mov_b64_e32 v[228:229], 0x5ff
	v_mov_b64_e32 v[232:233], 0x200
	v_mov_b64_e32 v[234:235], 0x1ff
	s_add_i32 s18, s23, 30
	s_cmp_ge_i32 s39, s18
	s_mov_b64 s[18:19], -1
	s_cbranch_scc0 .LBB0_229
	s_branch .LBB0_223
